# nt cache policy on the read-once f32 weight and x loads of P0 (and of the deferred transposes)
# speedup vs baseline: 1.0333x; 1.0202x over previous
; #define LAS __attribute__((address_space(3)))
; __device__ __forceinline__ unsigned pk2(float lo, float hi) { unsigned r; asm("v_cvt_pk_bf16_f32 %0, %1, %2" : "=v"(r) : "v"(lo), "v"(hi)); return r; }
; __device__ __forceinline__ void p0_transpose_item(const float* W, int K, int N, bf16_t* WT, int k0, int n0, int drow0, LAS float* scr, int lane, const float* kscale = nullptr) {
;     const float ks = kscale ? kscale[k0 + lane] : 1.f;
; #pragma unroll 8
;     for (int i = 0; i < 32; ++i) { const int kk = 2 * i + (lane >> 5); scr[kk * 33 + (lane & 31)] = W[(size_t)(k0 + kk) * N + n0 + (lane & 31)] * __shfl(ks, kk); }
;     asm volatile("s_waitcnt lgkmcnt(0)" ::: "memory");
;     const int c = lane & 7;
; #pragma unroll
;     for (int j = 0; j < 4; ++j) { const int n = (lane >> 3) + 8 * j; const LAS float* s = scr + (8 * c) * 33 + n;
;         u32x4 o; o.x = pk2(s[0 * 33], s[1 * 33]); o.y = pk2(s[2 * 33], s[3 * 33]); o.z = pk2(s[4 * 33], s[5 * 33]); o.w = pk2(s[6 * 33], s[7 * 33]);
;         *(u32x4*)(WT + (size_t)(drow0 + n) * K + k0 + 8 * c) = o; }
;     asm volatile("s_waitcnt lgkmcnt(0)" ::: "memory");
; }
.Lp0t_pro_scaled:
	global_load_dwordx4 v[40:43], v20, s[26:27] nt
	s_add_u32 s26, s26, s29
	s_addc_u32 s27, s27, 0
	global_load_dwordx4 v[44:47], v20, s[26:27] nt
	s_add_u32 s26, s26, s29
	s_addc_u32 s27, s27, 0
	global_load_dwordx4 v[48:51], v20, s[26:27] nt
	s_add_u32 s26, s26, s29
	s_addc_u32 s27, s27, 0
	global_load_dwordx4 v[52:55], v20, s[26:27] nt
	s_add_u32 s26, s26, s29
	s_addc_u32 s27, s27, 0
	global_load_dwordx4 v[56:59], v20, s[26:27] nt
	s_add_u32 s26, s26, s29
	s_addc_u32 s27, s27, 0
	global_load_dwordx4 v[60:63], v20, s[26:27] nt
	s_add_u32 s26, s26, s29
	s_addc_u32 s27, s27, 0
	global_load_dwordx4 v[64:67], v20, s[26:27] nt
	s_add_u32 s26, s26, s29
	s_addc_u32 s27, s27, 0
	global_load_dwordx4 v[68:71], v20, s[26:27] nt
	s_waitcnt vmcnt(0)
	ds_write_b128 v8, v[40:43] offset:0
	ds_write_b128 v9, v[44:47] offset:1024
	ds_write_b128 v10, v[48:51] offset:2048
	ds_write_b128 v11, v[52:55] offset:3072
	ds_write_b128 v12, v[56:59] offset:4096
	ds_write_b128 v13, v[60:63] offset:5120
	ds_write_b128 v14, v[64:67] offset:6144
	ds_write_b128 v15, v[68:71] offset:7168
	v_mov_b32_e32 v24, v32
	v_mov_b32_e32 v25, v33
	v_mov_b32_e32 v26, v34
	v_mov_b32_e32 v27, v35
	v_mov_b32_e32 v28, v36
	v_mov_b32_e32 v29, v37
	v_mov_b32_e32 v30, v38
	v_mov_b32_e32 v31, v39
	s_mov_b64 s[36:37], s[30:31]
	s_mov_b32 s38, s32
	s_waitcnt lgkmcnt(0)
	s_add_u32 s11, s11, s10

; #define LAS __attribute__((address_space(3)))
; __device__ __forceinline__ unsigned pk2(float lo, float hi) { unsigned r; asm("v_cvt_pk_bf16_f32 %0, %1, %2" : "=v"(r) : "v"(lo), "v"(hi)); return r; }
; __device__ __forceinline__ void p0_transpose_item(const float* W, int K, int N, bf16_t* WT, int k0, int n0, int drow0, LAS float* scr, int lane, const float* kscale = nullptr) {
;     const float ks = kscale ? kscale[k0 + lane] : 1.f;
; #pragma unroll 8
;     for (int i = 0; i < 32; ++i) { const int kk = 2 * i + (lane >> 5); scr[kk * 33 + (lane & 31)] = W[(size_t)(k0 + kk) * N + n0 + (lane & 31)] * __shfl(ks, kk); }
;     asm volatile("s_waitcnt lgkmcnt(0)" ::: "memory");
;     const int c = lane & 7;
; #pragma unroll
;     for (int j = 0; j < 4; ++j) { const int n = (lane >> 3) + 8 * j; const LAS float* s = scr + (8 * c) * 33 + n;
;         u32x4 o; o.x = pk2(s[0 * 33], s[1 * 33]); o.y = pk2(s[2 * 33], s[3 * 33]); o.z = pk2(s[4 * 33], s[5 * 33]); o.w = pk2(s[6 * 33], s[7 * 33]);
;         *(u32x4*)(WT + (size_t)(drow0 + n) * K + k0 + 8 * c) = o; }
;     asm volatile("s_waitcnt lgkmcnt(0)" ::: "memory");
; }
.Lp0t_main_scaled:
	global_load_dwordx4 v[40:43], v20, s[26:27] nt
	s_add_u32 s26, s26, s29
	s_addc_u32 s27, s27, 0
	global_load_dwordx4 v[44:47], v20, s[26:27] nt
	s_add_u32 s26, s26, s29
	s_addc_u32 s27, s27, 0
	global_load_dwordx4 v[48:51], v20, s[26:27] nt
	s_add_u32 s26, s26, s29
	s_addc_u32 s27, s27, 0
	global_load_dwordx4 v[52:55], v20, s[26:27] nt
	s_add_u32 s26, s26, s29
	s_addc_u32 s27, s27, 0
	global_load_dwordx4 v[56:59], v20, s[26:27] nt
	s_add_u32 s26, s26, s29
	s_addc_u32 s27, s27, 0
	global_load_dwordx4 v[60:63], v20, s[26:27] nt
	s_add_u32 s26, s26, s29
	s_addc_u32 s27, s27, 0
	global_load_dwordx4 v[64:67], v20, s[26:27] nt
	s_add_u32 s26, s26, s29
	s_addc_u32 s27, s27, 0
	global_load_dwordx4 v[68:71], v20, s[26:27] nt
	ds_read2_b32 v[72:73], v16 offset0:0 offset1:32
	ds_read2_b32 v[74:75], v16 offset0:64 offset1:96
	ds_read2_b32 v[76:77], v16 offset0:128 offset1:160
	ds_read2_b32 v[78:79], v16 offset0:192 offset1:224
	ds_read2_b32 v[80:81], v17 offset0:0 offset1:32
	ds_read2_b32 v[82:83], v17 offset0:64 offset1:96
	ds_read2_b32 v[84:85], v17 offset0:128 offset1:160
	ds_read2_b32 v[86:87], v17 offset0:192 offset1:224
	ds_read2_b32 v[88:89], v18 offset0:0 offset1:32
	ds_read2_b32 v[90:91], v18 offset0:64 offset1:96
	ds_read2_b32 v[92:93], v18 offset0:128 offset1:160
	ds_read2_b32 v[94:95], v18 offset0:192 offset1:224
	v_mad_u32_u24 v21, v4, s38, v5
	s_lshl_b32 s39, s38, 3
	ds_read2_b32 v[96:97], v19 offset0:0 offset1:32
	ds_read2_b32 v[98:99], v19 offset0:64 offset1:96
	ds_read2_b32 v[100:101], v19 offset0:128 offset1:160
	ds_read2_b32 v[102:103], v19 offset0:192 offset1:224
	s_waitcnt lgkmcnt(12)
	v_mul_f32_e32 v72, v72, v24
	v_mul_f32_e32 v73, v73, v25
	v_mul_f32_e32 v74, v74, v26
	v_mul_f32_e32 v75, v75, v27
	v_mul_f32_e32 v76, v76, v28
	v_mul_f32_e32 v77, v77, v29
	v_mul_f32_e32 v78, v78, v30
	v_mul_f32_e32 v79, v79, v31
	v_cvt_pk_bf16_f32 v72, v72, v73
	v_cvt_pk_bf16_f32 v73, v74, v75
	v_cvt_pk_bf16_f32 v74, v76, v77
	v_cvt_pk_bf16_f32 v75, v78, v79
	global_store_dwordx4 v21, v[72:75], s[36:37]
	s_add_u32 s36, s36, s39
	s_addc_u32 s37, s37, 0
	s_waitcnt lgkmcnt(8)
	v_mul_f32_e32 v80, v80, v24
	v_mul_f32_e32 v81, v81, v25
	v_mul_f32_e32 v82, v82, v26
	v_mul_f32_e32 v83, v83, v27
	v_mul_f32_e32 v84, v84, v28
	v_mul_f32_e32 v85, v85, v29
	v_mul_f32_e32 v86, v86, v30
	v_mul_f32_e32 v87, v87, v31
	v_cvt_pk_bf16_f32 v80, v80, v81
	v_cvt_pk_bf16_f32 v81, v82, v83
	v_cvt_pk_bf16_f32 v82, v84, v85
	v_cvt_pk_bf16_f32 v83, v86, v87
	global_store_dwordx4 v21, v[80:83], s[36:37]
	s_add_u32 s36, s36, s39
	s_addc_u32 s37, s37, 0
	s_waitcnt lgkmcnt(4)
	v_mul_f32_e32 v88, v88, v24
	v_mul_f32_e32 v89, v89, v25
	v_mul_f32_e32 v90, v90, v26
	v_mul_f32_e32 v91, v91, v27
	v_mul_f32_e32 v92, v92, v28
	v_mul_f32_e32 v93, v93, v29
	v_mul_f32_e32 v94, v94, v30
	v_mul_f32_e32 v95, v95, v31
	v_cvt_pk_bf16_f32 v88, v88, v89
	v_cvt_pk_bf16_f32 v89, v90, v91
	v_cvt_pk_bf16_f32 v90, v92, v93
	v_cvt_pk_bf16_f32 v91, v94, v95
	global_store_dwordx4 v21, v[88:91], s[36:37]
	s_add_u32 s36, s36, s39
	s_addc_u32 s37, s37, 0
	s_waitcnt lgkmcnt(0)
	v_mul_f32_e32 v96, v96, v24
	v_mul_f32_e32 v97, v97, v25
	v_mul_f32_e32 v98, v98, v26
	v_mul_f32_e32 v99, v99, v27
	v_mul_f32_e32 v100, v100, v28
	v_mul_f32_e32 v101, v101, v29
	v_mul_f32_e32 v102, v102, v30
	v_mul_f32_e32 v103, v103, v31
	v_cvt_pk_bf16_f32 v96, v96, v97
	v_cvt_pk_bf16_f32 v97, v98, v99
	v_cvt_pk_bf16_f32 v98, v100, v101
	v_cvt_pk_bf16_f32 v99, v102, v103
	global_store_dwordx4 v21, v[96:99], s[36:37]
	s_waitcnt vmcnt(4)
	ds_write_b128 v8, v[40:43] offset:0
	ds_write_b128 v9, v[44:47] offset:1024
	ds_write_b128 v10, v[48:51] offset:2048
	ds_write_b128 v11, v[52:55] offset:3072
	ds_write_b128 v12, v[56:59] offset:4096
	ds_write_b128 v13, v[60:63] offset:5120
	ds_write_b128 v14, v[64:67] offset:6144
	ds_write_b128 v15, v[68:71] offset:7168
	v_mov_b32_e32 v24, v32
	v_mov_b32_e32 v25, v33
	v_mov_b32_e32 v26, v34
	v_mov_b32_e32 v27, v35
	v_mov_b32_e32 v28, v36
	v_mov_b32_e32 v29, v37
	v_mov_b32_e32 v30, v38
	v_mov_b32_e32 v31, v39
	s_mov_b64 s[36:37], s[30:31]
	s_mov_b32 s38, s32
	s_waitcnt lgkmcnt(0)
	s_add_u32 s11, s11, s10
	s_branch .Lp0t_loop

; __device__ __forceinline__ unsigned pk2(float lo, float hi) { unsigned r; asm("v_cvt_pk_bf16_f32 %0, %1, %2" : "=v"(r) : "v"(lo), "v"(hi)); return r; }
; __device__ __forceinline__ void rms_row_to_bf16(const float* xrow, const float* w, bf16_t* orow, int lane) {
;     f32x4 v[8], ww[8]; float s = 0.f;
; #pragma unroll
;     for (int j = 0; j < 8; ++j) { v[j] = *(const f32x4*)(xrow + (j * 64 + lane) * 4); ww[j] = *(const f32x4*)(w + (j * 64 + lane) * 4); }
; #pragma unroll
;     for (int j = 0; j < 8; ++j) s += (v[j].x * v[j].x + v[j].y * v[j].y) + (v[j].z * v[j].z + v[j].w * v[j].w);
;     const float r = rsqrtf(wave_sum(s) * (1.f / DM) + EPS);
; #pragma unroll
;     for (int j = 0; j < 8; ++j) {
;         u32x2 o; o.x = pk2(v[j].x * r * ww[j].x, v[j].y * r * ww[j].y); o.y = pk2(v[j].z * r * ww[j].z, v[j].w * r * ww[j].w);
;         *(u32x2*)(orow + (j * 64 + lane) * 4) = o; }
; }
; __global__ void __launch_bounds__(512, 2) mk_fwd(Args args) {
;     ...
;         for (int m = gr; m < MT; m += NGW) { const float* xr = (m < MP) ? x_prompt + (size_t)m * DM : x_sample + (size_t)(m - MP) * DM; rms_row_to_bf16(xr, norm_mix_w, XN + (size_t)m * DM, lane); }
.LBB0_56:
	global_load_dwordx4 v[28:31], v50, s[18:19] nt
	global_load_dwordx4 v[20:23], v50, s[18:19] offset:1024 nt
	global_load_dwordx4 v[16:19], v50, s[18:19] offset:2048 nt
	global_load_dwordx4 v[12:15], v51, s[18:19] nt
	global_load_dwordx4 v[8:11], v52, s[18:19] nt
	global_load_dwordx4 v[24:27], v50, s[18:19] offset:3072 nt
	global_load_dwordx4 v[0:3], v54, s[18:19] nt
	global_load_dwordx4 v[4:7], v53, s[18:19] nt
	global_load_dwordx4 v[56:59], v[32:33], off
	global_load_dwordx4 v[60:63], v[32:33], off offset:1024
	global_load_dwordx4 v[64:67], v[32:33], off offset:2048
	global_load_dwordx4 v[68:71], v[32:33], off offset:3072
	global_load_dwordx4 v[72:75], v[34:35], off
	s_lshl_b64 s[16:17], s[16:17], 12
	s_add_u32 s4, s4, s10
	s_addc_u32 s5, s5, s11
	s_add_u32 s12, s12, s14
	s_addc_u32 s13, s13, s15
	s_cmpk_lt_i32 s4, 0x2200
	s_waitcnt vmcnt(12)
	v_mov_b32_e32 v78, v29
	s_waitcnt vmcnt(11)
	v_mov_b32_e32 v79, v21
	v_mov_b32_e32 v82, v31
	v_mov_b32_e32 v83, v23
	v_mov_b32_e32 v76, v28
	v_mov_b32_e32 v77, v20
	v_mov_b32_e32 v80, v30
	v_mov_b32_e32 v81, v22
	s_waitcnt vmcnt(10)
	v_pk_mul_f32 v[84:85], v[18:19], v[18:19]
	v_pk_mul_f32 v[86:87], v[16:17], v[16:17]
	v_pk_mul_f32 v[78:79], v[78:79], v[78:79]
	v_pk_mul_f32 v[82:83], v[82:83], v[82:83]
	v_pk_mov_b32 v[100:101], v[86:87], v[84:85] op_sel:[1,0]
	v_mov_b32_e32 v87, v85
	v_pk_fma_f32 v[76:77], v[76:77], v[76:77], v[78:79]
	v_pk_fma_f32 v[78:79], v[80:81], v[80:81], v[82:83]
	s_waitcnt vmcnt(8)
	v_pk_mul_f32 v[88:89], v[10:11], v[10:11]
	v_pk_mul_f32 v[90:91], v[8:9], v[8:9]
	s_waitcnt vmcnt(7)
	v_mul_f32_e32 v92, v25, v25
	v_mul_f32_e32 v94, v27, v27
	v_pk_add_f32 v[80:81], v[100:101], v[86:87]
	v_pk_add_f32 v[76:77], v[76:77], v[78:79]
	v_mul_f32_e32 v99, v14, v14
	v_mul_f32_e32 v102, v15, v15
	v_mul_f32_e32 v105, v12, v12
	v_mul_f32_e32 v106, v13, v13
	v_pk_mov_b32 v[84:85], v[90:91], v[88:89] op_sel:[1,0]
	v_mov_b32_e32 v91, v89
	v_pk_fma_f32 v[88:89], v[24:25], v[24:25], v[92:93] op_sel_hi:[1,1,0]
	v_pk_fma_f32 v[92:93], v[26:27], v[26:27], v[94:95] op_sel_hi:[1,1,0]
	v_pk_add_f32 v[80:81], v[80:81], v[80:81] op_sel:[0,1] op_sel_hi:[1,0]
	v_pk_add_f32 v[76:77], v[76:77], v[76:77] op_sel:[0,1] op_sel_hi:[1,0]
	v_mov_b32_e32 v89, v99
	v_mov_b32_e32 v93, v102
	v_mov_b32_e32 v81, v106
	v_mov_b32_e32 v77, v105
	v_pk_add_f32 v[78:79], v[88:89], v[92:93]
	v_pk_add_f32 v[76:77], v[76:77], v[80:81]
	s_waitcnt vmcnt(5)
	v_mul_f32_e32 v96, v5, v5
	v_mul_f32_e32 v98, v7, v7
	v_pk_add_f32 v[82:83], v[84:85], v[90:91]
	v_pk_add_f32 v[76:77], v[76:77], v[78:79]
	v_mul_f32_e32 v103, v2, v2
	v_mul_f32_e32 v104, v3, v3
	v_mul_f32_e32 v107, v1, v1
	v_mul_f32_e32 v108, v0, v0
	v_pk_fma_f32 v[94:95], v[4:5], v[4:5], v[96:97] op_sel_hi:[1,1,0]
	v_pk_fma_f32 v[96:97], v[6:7], v[6:7], v[98:99] op_sel_hi:[1,1,0]
	v_pk_add_f32 v[82:83], v[82:83], v[82:83] op_sel:[0,1] op_sel_hi:[1,0]
	v_pk_add_f32 v[76:77], v[76:77], v[76:77] op_sel:[0,1] op_sel_hi:[1,0]
	v_mov_b32_e32 v95, v103
	v_mov_b32_e32 v97, v104
	v_mov_b32_e32 v83, v107
	v_mov_b32_e32 v77, v108
	v_pk_add_f32 v[84:85], v[94:95], v[96:97]
	v_pk_add_f32 v[76:77], v[76:77], v[82:83]
	v_lshl_add_u64 v[88:89], v[42:43], 0, s[16:17]
	v_pk_add_f32 v[76:77], v[76:77], v[84:85]
	s_nop 0
	v_add_f32_e32 v76, v76, v77
	ds_bpermute_b32 v77, v44, v76
	s_waitcnt lgkmcnt(0)
	v_add_f32_e32 v76, v76, v77
	ds_bpermute_b32 v77, v45, v76
	s_waitcnt lgkmcnt(0)
	v_add_f32_e32 v76, v76, v77
	ds_bpermute_b32 v77, v46, v76
	s_waitcnt lgkmcnt(0)
; __device__ __forceinline__ unsigned pk2(float lo, float hi) { unsigned r; asm("v_cvt_pk_bf16_f32 %0, %1, %2" : "=v"(r) : "v"(lo), "v"(hi)); return r; }
; __device__ __forceinline__ void rms_row_to_bf16(const float* xrow, const float* w, bf16_t* orow, int lane) {
;     f32x4 v[8], ww[8]; float s = 0.f;
; #pragma unroll
;     for (int j = 0; j < 8; ++j) { v[j] = *(const f32x4*)(xrow + (j * 64 + lane) * 4); ww[j] = *(const f32x4*)(w + (j * 64 + lane) * 4); }
; #pragma unroll
;     for (int j = 0; j < 8; ++j) s += (v[j].x * v[j].x + v[j].y * v[j].y) + (v[j].z * v[j].z + v[j].w * v[j].w);
;     const float r = rsqrtf(wave_sum(s) * (1.f / DM) + EPS);
; #pragma unroll
;     for (int j = 0; j < 8; ++j) {
;         u32x2 o; o.x = pk2(v[j].x * r * ww[j].x, v[j].y * r * ww[j].y); o.y = pk2(v[j].z * r * ww[j].z, v[j].w * r * ww[j].w);
;         *(u32x2*)(orow + (j * 64 + lane) * 4) = o; }
; }
	v_add_f32_e32 v80, v76, v77
	ds_bpermute_b32 v81, v47, v80
	global_load_dwordx4 v[76:79], v[36:37], off
	s_waitcnt lgkmcnt(0)
	v_add_f32_e32 v80, v80, v81
	ds_bpermute_b32 v81, v48, v80
	s_waitcnt lgkmcnt(0)
	v_add_f32_e32 v84, v80, v81
	ds_bpermute_b32 v85, v49, v84
	global_load_dwordx4 v[80:83], v[38:39], off
	s_waitcnt lgkmcnt(0)
	v_add_f32_e32 v84, v84, v85
	v_fmamk_f32 v84, v84, 0x3a000000, v55
	v_mul_f32_e32 v85, 0x4b800000, v84
	v_cmp_gt_f32_e32 vcc, s3, v84
	s_nop 1
	v_cndmask_b32_e32 v84, v84, v85, vcc
	v_rsq_f32_e32 v90, v84
	global_load_dwordx4 v[84:87], v[40:41], off
	v_mul_f32_e32 v91, 0x45800000, v90
	v_cndmask_b32_e32 v90, v90, v91, vcc
	v_mul_f32_e32 v28, v28, v90
	v_mul_f32_e32 v29, v29, v90
	v_mul_f32_e32 v30, v30, v90
	v_mul_f32_e32 v31, v31, v90
	v_mul_f32_e32 v20, v20, v90
	v_mul_f32_e32 v21, v21, v90
	v_mul_f32_e32 v19, v19, v90
	v_mul_f32_e32 v12, v12, v90
	v_mul_f32_e32 v91, v13, v90
	s_waitcnt vmcnt(7)
	v_mul_f32_e32 v13, v56, v28
	v_mul_f32_e32 v8, v8, v90
	v_mul_f32_e32 v9, v9, v90
	v_mul_f32_e32 v4, v4, v90
	v_mul_f32_e32 v5, v5, v90
	v_mul_f32_e32 v0, v0, v90
	v_mul_f32_e32 v1, v1, v90
	v_mul_f32_e32 v22, v22, v90
	v_mul_f32_e32 v23, v23, v90
	v_mul_f32_e32 v16, v16, v90
	v_mul_f32_e32 v17, v17, v90
	v_mul_f32_e32 v18, v18, v90
	v_mul_f32_e32 v24, v24, v90
	v_mul_f32_e32 v25, v25, v90
	v_mul_f32_e32 v26, v26, v90
	v_mul_f32_e32 v27, v27, v90
	v_mul_f32_e32 v28, v57, v29
	v_mul_f32_e32 v29, v58, v30
	v_mul_f32_e32 v30, v59, v31
	s_waitcnt vmcnt(6)
	v_mul_f32_e32 v20, v60, v20
	v_mul_f32_e32 v21, v61, v21
	s_waitcnt vmcnt(5)
	v_mul_f32_e32 v19, v67, v19
	s_waitcnt vmcnt(3)
	v_mul_f32_e32 v58, v72, v12
	v_cvt_pk_bf16_f32 v12, v13, v28
	v_cvt_pk_bf16_f32 v13, v29, v30
	v_mul_f32_e32 v22, v62, v22
	v_mul_f32_e32 v23, v63, v23
	v_mul_f32_e32 v31, v64, v16
	v_mul_f32_e32 v56, v65, v17
	v_mul_f32_e32 v57, v66, v18
	v_mul_f32_e32 v24, v68, v24
	v_mul_f32_e32 v25, v69, v25
	v_mul_f32_e32 v26, v70, v26
	v_mul_f32_e32 v27, v71, v27
	v_cvt_pk_bf16_f32 v16, v20, v21
	v_cvt_pk_bf16_f32 v17, v22, v23
	v_cvt_pk_bf16_f32 v18, v31, v56
	v_cvt_pk_bf16_f32 v19, v57, v19
	v_cvt_pk_bf16_f32 v20, v24, v25
	v_cvt_pk_bf16_f32 v21, v26, v27
	global_store_dwordx2 v[88:89], v[12:13], off
	global_store_dwordx2 v[88:89], v[16:17], off offset:512
	global_store_dwordx2 v[88:89], v[18:19], off offset:1024
	global_store_dwordx2 v[88:89], v[20:21], off offset:1536
	v_mul_f32_e32 v13, v14, v90
	s_waitcnt vmcnt(6)
	v_mul_f32_e32 v8, v76, v8
	v_mul_f32_e32 v9, v77, v9
	v_cvt_pk_bf16_f32 v8, v8, v9
	v_mul_f32_e32 v9, v10, v90
	v_mul_f32_e32 v12, v73, v91
	v_mul_f32_e32 v13, v74, v13
	v_mul_f32_e32 v14, v15, v90
	v_mul_f32_e32 v9, v78, v9
	v_mul_f32_e32 v10, v11, v90
	v_cvt_pk_bf16_f32 v12, v58, v12
	v_mul_f32_e32 v14, v75, v14
	v_cvt_pk_bf16_f32 v13, v13, v14
	s_waitcnt vmcnt(5)
	v_mul_f32_e32 v4, v80, v4
	v_mul_f32_e32 v5, v81, v5
	v_cvt_pk_bf16_f32 v4, v4, v5
	v_mul_f32_e32 v5, v6, v90
	v_mul_f32_e32 v5, v82, v5
	v_mul_f32_e32 v6, v7, v90
	global_store_dwordx2 v[88:89], v[12:13], off offset:2048
	v_mul_f32_e32 v10, v79, v10
	v_cvt_pk_bf16_f32 v9, v9, v10
	global_store_dwordx2 v[88:89], v[8:9], off offset:2560
	v_mul_f32_e32 v6, v83, v6
	v_cvt_pk_bf16_f32 v5, v5, v6
	s_waitcnt vmcnt(6)
	v_mul_f32_e32 v0, v84, v0
	v_mul_f32_e32 v1, v85, v1
	v_cvt_pk_bf16_f32 v0, v0, v1
	v_mul_f32_e32 v1, v2, v90
	v_mul_f32_e32 v1, v86, v1
	v_mul_f32_e32 v2, v3, v90
	global_store_dwordx2 v[88:89], v[4:5], off offset:3072
	v_mul_f32_e32 v2, v87, v2
	v_cvt_pk_bf16_f32 v1, v1, v2
	global_store_dwordx2 v[88:89], v[0:1], off offset:3584
	s_cbranch_scc0 .LBB0_61
